# GDN prep: gate cumsum by DPP row_shr/row_bcast scan instead of 6 bpermute rounds; LDS reads hoisted in the KK^T and solve segments
# baseline (speedup 1.0000x reference)
; DI float bf2f(bf16_t b) { return __uint_as_float(((unsigned)b) << 16); }
; DI void gdn_prep_item(const P& p, int l, int item, unsigned char* smem) {
;     ...
;     {
;         const bf16_t* Rb = w < 4 ? sVb : sKEb;
;         bf16_t* dstb = (w < 4 ? U : W) + ((size_t)seq * PT + 64 * c) * 128;
; #pragma unroll
;         for (int n2 = 0; n2 < 2; ++n2) {
;             const int col0 = 32 * (w & 3) + 16 * n2;
;             s16x4 Xb[4];
; #pragma unroll
;             for (int I = 0; I < 4; ++I) {
;                 f32x4 accL = (f32x4){0.f, 0.f, 0.f, 0.f};
; #pragma unroll
;                 for (int J = 0; J < I; ++J)
;                     accL = __builtin_amdgcn_mfma_f32_16x16x16bf16_1k(*(const s16x4*)(sLb + (16 * I + l15) * 72 + 16 * J + 4 * g), Xb[J], accL, 0, 0, 0);
;                 f32x4 rhs;
; #pragma unroll
;                 for (int r = 0; r < 4; ++r) rhs[r] = bf2f(Rb[(16 * I + 4 * g + r) * 136 + col0 + l15]) - accL[r];
;                 u32x2 pb; pb.x = pk2(rhs[0], rhs[1]); pb.y = pk2(rhs[2], rhs[3]);
;                 const f32x4 X = __builtin_amdgcn_mfma_f32_16x16x16bf16_1k(*(const s16x4*)(sTd + (I * 16 + l15) * 24 + 4 * g), __builtin_bit_cast(s16x4, pb), (f32x4){0.f, 0.f, 0.f, 0.f}, 0, 0, 0);
;                 u32x2 px; px.x = pk2(X[0], X[1]); px.y = pk2(X[2], X[3]);
;                 Xb[I] = __builtin_bit_cast(s16x4, px);
; #pragma unroll
;                 for (int r = 0; r < 4; ++r) dstb[(size_t)(16 * I + 4 * g + r) * 128 + col0 + l15] = f2bf(X[r]);
;             }
;         }
;     }
.LBB0_321:
	s_or_b64 exec, exec, vcc
	s_waitcnt lgkmcnt(0)
	s_barrier
	ds_read2_b64 v[228:231], v199 offset1:96
	ds_read_u16 v232, v164
	ds_read_u16 v233, v165
	ds_read_u16 v234, v183
	ds_read_u16 v235, v184
	ds_read_b64 v[236:237], v200
	ds_read_u16 v238, v185
	ds_read_u16 v239, v186
	ds_read_u16 v240, v187
	ds_read_u16 v241, v188
	ds_read_u16 v242, v189
	ds_read_u16 v243, v190
	s_xor_b64 vcc, s[36:37], -1
	s_waitcnt lgkmcnt(10)
	v_lshlrev_b32_e32 v16, 16, v232
	ds_read_u16 v248, v191
	ds_read_u16 v249, v192
	s_waitcnt lgkmcnt(11)
	v_lshlrev_b32_e32 v17, 16, v233
	ds_read_u16 v250, v193
	s_waitcnt lgkmcnt(11)
	v_lshlrev_b32_e32 v18, 16, v234
	ds_read_u16 v251, v194
	s_waitcnt lgkmcnt(11)
	v_lshlrev_b32_e32 v19, 16, v235
	s_ashr_i32 s5, s31, 31
	v_cvt_pk_bf16_f32 v16, v16, v17
	v_cvt_pk_bf16_f32 v17, v18, v19
	s_add_u32 s4, s3, s31
	s_nop 0
	v_mfma_f32_16x16x16_bf16 v[16:19], v[228:229], v[16:17], 0
	s_addc_u32 s5, s2, s5
	s_lshl_b64 s[2:3], s[4:5], 8
	s_add_u32 s36, s85, s2
	s_addc_u32 s37, s86, s3
	v_lshlrev_b32_e32 v213, 1, v90
	s_nop 2
	v_cvt_pk_bf16_f32 v20, v16, s0
	v_cvt_pk_bf16_f32 v21, v17, s0
	v_cvt_pk_bf16_f32 v122, v16, v17
	v_cvt_pk_bf16_f32 v16, v18, s0
	v_cvt_pk_bf16_f32 v17, v19, s0
	v_lshlrev_b32_e32 v214, 1, v92
	v_lshlrev_b32_e32 v215, 1, v94
	v_lshlrev_b32_e32 v216, 1, v96
	global_store_short v213, v20, s[36:37]
	global_store_short v214, v21, s[36:37]
	global_store_short v215, v16, s[36:37]
	global_store_short v216, v17, s[36:37]
	v_cvt_pk_bf16_f32 v123, v18, v19
	v_lshlrev_b32_e32 v211, 1, v102
	v_lshlrev_b32_e32 v212, 1, v104
	s_waitcnt lgkmcnt(10)
	v_mfma_f32_16x16x16_bf16 v[16:19], v[236:237], v[122:123], 0
	s_waitcnt lgkmcnt(8)
	v_lshlrev_b32_e32 v21, 16, v239
	ds_read_u16 v239, v195
	v_lshlrev_b32_e32 v20, 16, v238
	ds_read_u16 v238, v196
	v_lshlrev_b32_e32 v209, 1, v98
	v_lshlrev_b32_e32 v210, 1, v100
	v_lshlrev_b32_e32 v207, 1, v110
	s_nop 1
	v_pk_add_f32 v[16:17], v[20:21], v[16:17] neg_lo:[0,1] neg_hi:[0,1]
	v_lshlrev_b32_e32 v208, 1, v112
	v_cvt_pk_bf16_f32 v16, v16, v17
	v_lshlrev_b32_e32 v205, 1, v106
	v_lshlrev_b32_e32 v206, 1, v108
	s_mov_b32 s31, 1
	s_and_b64 vcc, exec, vcc
	s_waitcnt lgkmcnt(8)
	v_lshlrev_b32_e32 v21, 16, v241
	v_lshlrev_b32_e32 v20, 16, v240
	v_pk_add_f32 v[18:19], v[20:21], v[18:19] neg_lo:[0,1] neg_hi:[0,1]
	s_nop 0
	v_cvt_pk_bf16_f32 v17, v18, v19
	s_nop 1
	v_mfma_f32_16x16x16_bf16 v[16:19], v[230:231], v[16:17], 0
	s_nop 7
	v_cvt_pk_bf16_f32 v20, v16, s0
	v_cvt_pk_bf16_f32 v134, v16, v17
	v_cvt_pk_bf16_f32 v16, v18, s0
	global_store_short v211, v16, s[36:37]
	v_add_u32_e32 v16, 0x800, v200
	ds_read2_b64 v[244:247], v16 offset0:32 offset1:36
	v_cvt_pk_bf16_f32 v21, v17, s0
	v_cvt_pk_bf16_f32 v17, v19, s0
	v_cvt_pk_bf16_f32 v135, v18, v19
	global_store_short v212, v17, s[36:37]
	s_waitcnt lgkmcnt(0)
	v_mfma_f32_16x16x16_bf16 v[16:19], v[244:245], v[122:123], 0
	global_store_short v209, v20, s[36:37]
	global_store_short v210, v21, s[36:37]
	v_mfma_f32_16x16x16_bf16 v[16:19], v[246:247], v[134:135], v[16:19]
	v_lshlrev_b32_e32 v20, 16, v242
	v_lshlrev_b32_e32 v21, 16, v243
	s_nop 3
	s_nop 1
	v_pk_add_f32 v[16:17], v[20:21], v[16:17] neg_lo:[0,1] neg_hi:[0,1]
	s_nop 0
	v_cvt_pk_bf16_f32 v20, v16, v17
	v_lshlrev_b32_e32 v16, 16, v248
	ds_read_u16 v248, v164 offset:32
	v_lshlrev_b32_e32 v17, 16, v249
	ds_read_u16 v249, v165 offset:32
	v_pk_add_f32 v[16:17], v[16:17], v[18:19] neg_lo:[0,1] neg_hi:[0,1]
	s_nop 0
	v_cvt_pk_bf16_f32 v21, v16, v17
	v_add_u32_e32 v16, 0x400, v199
	ds_read2_b64 v[232:235], v16 offset0:64 offset1:160
	s_waitcnt lgkmcnt(0)
	v_mfma_f32_16x16x16_bf16 v[20:23], v[232:233], v[20:21], 0
	s_nop 7
	v_cvt_pk_bf16_f32 v201, v20, s0
	v_cvt_pk_bf16_f32 v202, v20, v21
	v_cvt_pk_bf16_f32 v20, v22, s0
	v_cvt_pk_bf16_f32 v204, v21, s0
	v_cvt_pk_bf16_f32 v21, v23, s0
	global_store_short v207, v20, s[36:37]
	v_add_u32_e32 v20, 0x1000, v200
	ds_read2_b64 v[240:243], v20 offset0:64 offset1:68
	v_cvt_pk_bf16_f32 v203, v22, v23
	global_store_short v208, v21, s[36:37]
	s_waitcnt lgkmcnt(0)
	v_mfma_f32_16x16x16_bf16 v[224:227], v[240:241], v[122:123], 0
	ds_read_b64 v[122:123], v200 offset:4672
	global_store_short v205, v201, s[36:37]
	global_store_short v206, v204, s[36:37]
	v_mfma_f32_16x16x16_bf16 v[224:227], v[242:243], v[134:135], v[224:227]
	v_lshlrev_b32_e32 v204, 1, v120
	v_lshlrev_b32_e32 v134, 16, v250
	ds_read_u16 v250, v183 offset:32
	s_waitcnt lgkmcnt(1)
; DI float bf2f(bf16_t b) { return __uint_as_float(((unsigned)b) << 16); }
; DI void gdn_prep_item(const P& p, int l, int item, unsigned char* smem) {
;     ...
;     {
;         const bf16_t* Rb = w < 4 ? sVb : sKEb;
;         bf16_t* dstb = (w < 4 ? U : W) + ((size_t)seq * PT + 64 * c) * 128;
; #pragma unroll
;         for (int n2 = 0; n2 < 2; ++n2) {
;             const int col0 = 32 * (w & 3) + 16 * n2;
;             s16x4 Xb[4];
; #pragma unroll
;             for (int I = 0; I < 4; ++I) {
;                 f32x4 accL = (f32x4){0.f, 0.f, 0.f, 0.f};
; #pragma unroll
;                 for (int J = 0; J < I; ++J)
;                     accL = __builtin_amdgcn_mfma_f32_16x16x16bf16_1k(*(const s16x4*)(sLb + (16 * I + l15) * 72 + 16 * J + 4 * g), Xb[J], accL, 0, 0, 0);
;                 f32x4 rhs;
; #pragma unroll
;                 for (int r = 0; r < 4; ++r) rhs[r] = bf2f(Rb[(16 * I + 4 * g + r) * 136 + col0 + l15]) - accL[r];
;                 u32x2 pb; pb.x = pk2(rhs[0], rhs[1]); pb.y = pk2(rhs[2], rhs[3]);
;                 const f32x4 X = __builtin_amdgcn_mfma_f32_16x16x16bf16_1k(*(const s16x4*)(sTd + (I * 16 + l15) * 24 + 4 * g), __builtin_bit_cast(s16x4, pb), (f32x4){0.f, 0.f, 0.f, 0.f}, 0, 0, 0);
;                 u32x2 px; px.x = pk2(X[0], X[1]); px.y = pk2(X[2], X[3]);
;                 Xb[I] = __builtin_bit_cast(s16x4, px);
; #pragma unroll
;                 for (int r = 0; r < 4; ++r) dstb[(size_t)(16 * I + 4 * g + r) * 128 + col0 + l15] = f2bf(X[r]);
;             }
;         }
;     }
	v_mfma_f32_16x16x16_bf16 v[224:227], v[122:123], v[202:203], v[224:227]
	v_lshlrev_b32_e32 v135, 16, v251
	ds_read_u16 v251, v184 offset:32
	s_nop 5
	v_pk_add_f32 v[134:135], v[134:135], v[224:225] neg_lo:[0,1] neg_hi:[0,1]
	s_nop 0
	v_cvt_pk_bf16_f32 v134, v134, v135
	v_lshlrev_b32_e32 v202, 16, v239
	ds_read_u16 v239, v185 offset:32
	v_lshlrev_b32_e32 v203, 16, v238
	ds_read_u16 v238, v186 offset:32
	v_pk_add_f32 v[202:203], v[202:203], v[226:227] neg_lo:[0,1] neg_hi:[0,1]
	v_lshlrev_b32_e32 v201, 1, v114
	v_cvt_pk_bf16_f32 v135, v202, v203
	v_lshlrev_b32_e32 v202, 1, v116
	v_lshlrev_b32_e32 v203, 1, v118
	v_mfma_f32_16x16x16_bf16 v[224:227], v[234:235], v[134:135], 0
	s_nop 7
	v_cvt_pk_bf16_f32 v134, v224, s0
	global_store_short v201, v134, s[36:37]
	v_cvt_pk_bf16_f32 v134, v225, s0
	global_store_short v202, v134, s[36:37]
	v_cvt_pk_bf16_f32 v134, v226, s0
	global_store_short v203, v134, s[36:37]
	v_cvt_pk_bf16_f32 v134, v227, s0
	global_store_short v204, v134, s[36:37]
	v_lshlrev_b32_e32 v217, 16, v248
	ds_read_u16 v248, v187 offset:32
	v_lshlrev_b32_e32 v218, 16, v249
	ds_read_u16 v249, v188 offset:32
	s_waitcnt lgkmcnt(5)
	v_lshlrev_b32_e32 v219, 16, v250
	ds_read_u16 v250, v189 offset:32
	s_waitcnt lgkmcnt(5)
	v_lshlrev_b32_e32 v135, 16, v251
	ds_read_u16 v251, v190 offset:32
	v_cvt_pk_bf16_f32 v134, v217, v218
	v_cvt_pk_bf16_f32 v135, v219, v135
	s_nop 1
	v_mfma_f32_16x16x16_bf16 v[224:227], v[228:229], v[134:135], 0
	s_nop 7
	v_cvt_pk_bf16_f32 v134, v224, s0
	v_cvt_pk_bf16_f32 v135, v225, s0
	v_cvt_pk_bf16_f32 v24, v224, v225
	v_cvt_pk_bf16_f32 v217, v226, s0
	v_cvt_pk_bf16_f32 v218, v227, s0
	v_cvt_pk_bf16_f32 v25, v226, v227
	global_store_short v213, v134, s[36:37] offset:32
	global_store_short v214, v135, s[36:37] offset:32
	global_store_short v215, v217, s[36:37] offset:32
	global_store_short v216, v218, s[36:37] offset:32
	v_mfma_f32_16x16x16_bf16 v[214:217], v[236:237], v[24:25], 0
	ds_read_u16 v236, v191 offset:32
	ds_read_u16 v237, v192 offset:32
	s_waitcnt lgkmcnt(7)
	v_lshlrev_b32_e32 v124, 16, v239
	ds_read_u16 v239, v193 offset:32
	s_waitcnt lgkmcnt(7)
	v_lshlrev_b32_e32 v125, 16, v238
	ds_read_u16 v238, v194 offset:32
	s_nop 1
	v_pk_add_f32 v[124:125], v[124:125], v[214:215] neg_lo:[0,1] neg_hi:[0,1]
	s_nop 0
	v_cvt_pk_bf16_f32 v124, v124, v125
	s_waitcnt lgkmcnt(6)
	v_lshlrev_b32_e32 v135, 16, v249
	ds_read_u16 v249, v195 offset:32
	v_lshlrev_b32_e32 v134, 16, v248
	ds_read_u16 v248, v196 offset:32
	v_pk_add_f32 v[134:135], v[134:135], v[216:217] neg_lo:[0,1] neg_hi:[0,1]
	s_nop 0
	v_cvt_pk_bf16_f32 v125, v134, v135
	s_nop 1
	v_mfma_f32_16x16x16_bf16 v[214:217], v[230:231], v[124:125], 0
	s_nop 7
	v_cvt_pk_bf16_f32 v26, v214, s0
	v_cvt_pk_bf16_f32 v27, v215, s0
	v_cvt_pk_bf16_f32 v134, v216, s0
	v_cvt_pk_bf16_f32 v135, v217, s0
	global_store_short v209, v26, s[36:37] offset:32
	global_store_short v210, v27, s[36:37] offset:32
	global_store_short v211, v134, s[36:37] offset:32
	global_store_short v212, v135, s[36:37] offset:32
	v_mfma_f32_16x16x16_bf16 v[26:29], v[244:245], v[24:25], 0
	v_cvt_pk_bf16_f32 v124, v214, v215
	v_cvt_pk_bf16_f32 v125, v216, v217
	s_nop 1
	v_mfma_f32_16x16x16_bf16 v[26:29], v[246:247], v[124:125], v[26:29]
	s_waitcnt lgkmcnt(7)
	v_lshlrev_b32_e32 v30, 16, v250
	s_waitcnt lgkmcnt(6)
	v_lshlrev_b32_e32 v31, 16, v251
	s_nop 1
	s_nop 1
	v_pk_add_f32 v[26:27], v[30:31], v[26:27] neg_lo:[0,1] neg_hi:[0,1]
	s_nop 0
	v_cvt_pk_bf16_f32 v26, v26, v27
	s_waitcnt lgkmcnt(4)
	v_lshlrev_b32_e32 v31, 16, v237
	v_lshlrev_b32_e32 v30, 16, v236
	v_pk_add_f32 v[28:29], v[30:31], v[28:29] neg_lo:[0,1] neg_hi:[0,1]
	s_nop 0
	v_cvt_pk_bf16_f32 v27, v28, v29
	s_nop 1
	v_mfma_f32_16x16x16_bf16 v[26:29], v[232:233], v[26:27], 0
	s_nop 7
	v_cvt_pk_bf16_f32 v30, v26, s0
	v_cvt_pk_bf16_f32 v31, v27, s0
	v_cvt_pk_bf16_f32 v16, v26, v27
	v_cvt_pk_bf16_f32 v26, v28, s0
	v_cvt_pk_bf16_f32 v27, v29, s0
	global_store_short v205, v30, s[36:37] offset:32
	global_store_short v206, v31, s[36:37] offset:32
	global_store_short v207, v26, s[36:37] offset:32
	global_store_short v208, v27, s[36:37] offset:32
	v_mfma_f32_16x16x16_bf16 v[24:27], v[240:241], v[24:25], 0
	v_cvt_pk_bf16_f32 v17, v28, v29
	v_mfma_f32_16x16x16_bf16 v[20:23], v[242:243], v[124:125], v[24:27]
	s_nop 0
	v_mfma_f32_16x16x16_bf16 v[20:23], v[122:123], v[16:17], v[20:23]
	s_waitcnt lgkmcnt(3)
	v_lshlrev_b32_e32 v16, 16, v239
	s_waitcnt lgkmcnt(2)
	v_lshlrev_b32_e32 v17, 16, v238
	s_nop 1
	s_nop 1
	v_pk_add_f32 v[16:17], v[16:17], v[20:21] neg_lo:[0,1] neg_hi:[0,1]
	s_nop 0
	v_cvt_pk_bf16_f32 v16, v16, v17
	s_waitcnt lgkmcnt(0)
	v_lshlrev_b32_e32 v21, 16, v248
	v_lshlrev_b32_e32 v20, 16, v249
	v_pk_add_f32 v[20:21], v[20:21], v[22:23] neg_lo:[0,1] neg_hi:[0,1]
	s_nop 0
	v_cvt_pk_bf16_f32 v17, v20, v21
	s_nop 1
	v_mfma_f32_16x16x16_bf16 v[16:19], v[234:235], v[16:17], 0
	s_nop 7
	v_cvt_pk_bf16_f32 v16, v16, s0
	global_store_short v201, v16, s[36:37] offset:32
	v_cvt_pk_bf16_f32 v16, v17, s0
	global_store_short v202, v16, s[36:37] offset:32
	v_cvt_pk_bf16_f32 v16, v18, s0
	global_store_short v203, v16, s[36:37] offset:32
	v_cvt_pk_bf16_f32 v16, v19, s0
	global_store_short v204, v16, s[36:37] offset:32
	s_mov_b64 s[36:37], 0
	s_waitcnt vmcnt(63)
	s_barrier
	s_cbranch_vccnz .LBB0_330

; DI void gdn_prep_item(const P& p, int l, int item, unsigned char* smem) {
;     ...
;     if (tid < 64) {
;         float v = sg[tid];
; #pragma unroll
;         for (int o = 1; o < 64; o <<= 1) { const float u = __shfl_up(v, o); if (tid >= o) v += u; }
;         scum[tid] = v;
;     }
.LBB0_324:
	s_or_b64 exec, exec, s[82:83]
	s_waitcnt lgkmcnt(0)
	s_barrier
	s_and_saveexec_b64 s[82:83], s[38:39]
	s_cbranch_execz .LBB0_326
	ds_read_b32 v19, v113
	s_waitcnt lgkmcnt(0)
	s_nop 1
	v_add_f32_dpp v19, v19, v19 row_shr:1 row_mask:0xf bank_mask:0xf bound_ctrl:0
	s_nop 1
	v_add_f32_dpp v19, v19, v19 row_shr:2 row_mask:0xf bank_mask:0xf bound_ctrl:0
	s_nop 1
	v_add_f32_dpp v19, v19, v19 row_shr:4 row_mask:0xf bank_mask:0xf bound_ctrl:0
	s_nop 1
	v_add_f32_dpp v19, v19, v19 row_shr:8 row_mask:0xf bank_mask:0xf bound_ctrl:0
	s_nop 1
	v_add_f32_dpp v19, v19, v19 row_bcast:15 row_mask:0xa bank_mask:0xf
	s_nop 1
	v_add_f32_dpp v19, v19, v19 row_bcast:31 row_mask:0xc bank_mask:0xf
	ds_write_b32 v115, v19

; DI f32x4 mfma16(bf16x8 a, bf16x8 b, f32x4 c) { return __builtin_amdgcn_mfma_f32_16x16x32_bf16(a, b, c, 0, 0, 0); }
; DI void gdn_prep_item(const P& p, int l, int item, unsigned char* smem) {
;     ...
;         const int mt = w >> 1;
; #pragma unroll
;         for (int n2 = 0; n2 < 2; ++n2) {
;             const int nt = 2 * (w & 1) + n2;
;             f32x4 aL = (f32x4){0.f, 0.f, 0.f, 0.f}, aA = (f32x4){0.f, 0.f, 0.f, 0.f};
; #pragma unroll
;             for (int ks = 0; ks < 4; ++ks) {
;                 const bf16x8 bk = ld8(sK + (16 * nt + l15) * 136 + 32 * ks + 8 * g);
;                 aL = mfma16(bk, ld8(sKB + (16 * mt + l15) * 136 + 32 * ks + 8 * g), aL);
;                 aA = mfma16(bk, ld8(sQ + (16 * mt + l15) * 136 + 32 * ks + 8 * g), aA);
;             }
;             const int ii = 16 * mt + l15, j0 = 16 * nt + 4 * g;
;             const f32x4 cj = *(const f32x4*)(scum + j0); const float ci = scum[ii];
;             f32x4 lv; float av[4];
; #pragma unroll
;             for (int r = 0; r < 4; ++r) {
;                 const float dcy = __expf(fminf(ci - cj[r], 0.f));
;                 lv[r] = (j0 + r < ii) ? aL[r] * dcy : 0.f;
;                 av[r] = (j0 + r <= ii) ? aA[r] * dcy : 0.f;
;             }
;             *(f32x4*)(sL + ii * LS + j0) = lv;
;             { u32x2 lb; lb.x = pk2(lv[0], lv[1]); lb.y = pk2(lv[2], lv[3]); *(u32x2*)(sLb + ii * 72 + j0) = lb; }
;             { u32x2 ab; ab.x = pk2(av[0], av[1]); ab.y = pk2(av[2], av[3]); *(u32x2*)(AT + (((size_t)seq * 36 + c) * 64 + ii) * 64 + j0) = ab; }
;         }
;     }
.LBB0_328:
	s_or_b64 exec, exec, s[82:83]
	s_waitcnt lgkmcnt(0)
	s_barrier
	ds_read_b128 v[228:231], v197
	ds_read_b128 v[232:235], v107 offset:17408
	ds_read_b128 v[236:239], v107 offset:34816
	ds_read_b128 v[240:243], v197 offset:64
	ds_read_b128 v[244:247], v107 offset:17472
	ds_read_b128 v[248:251], v107 offset:34880
	s_waitcnt lgkmcnt(4)
	v_mfma_f32_16x16x32_bf16 v[20:23], v[228:231], v[232:235], 0
	ds_read_b128 v[232:235], v197 offset:128
	s_ashr_i32 s6, vcc_hi, 31
	s_mul_hi_i32 s5, vcc_lo, 36
	s_add_u32 s4, s20, vcc_hi
	s_waitcnt lgkmcnt(4)
	v_mfma_f32_16x16x32_bf16 v[16:19], v[228:231], v[236:239], 0
	ds_read_b128 v[228:231], v107 offset:17536
	ds_read_b128 v[236:239], v107 offset:34944
	s_addc_u32 s5, s5, s6
	s_lshl_b64 s[4:5], s[4:5], 13
	s_waitcnt lgkmcnt(4)
	v_mfma_f32_16x16x32_bf16 v[20:23], v[240:243], v[244:247], v[20:23]
	ds_read_b128 v[244:247], v197 offset:192
	v_lshl_add_u64 v[122:123], v[84:85], 0, s[4:5]
	s_waitcnt lgkmcnt(4)
	v_mfma_f32_16x16x32_bf16 v[16:19], v[240:243], v[248:251], v[16:19]
	ds_read_b128 v[240:243], v107 offset:17600
	ds_read_b128 v[248:251], v107 offset:35008
	s_waitcnt lgkmcnt(4)
	v_mfma_f32_16x16x32_bf16 v[20:23], v[232:235], v[228:231], v[20:23]
	ds_read_b128 v[228:231], v143
	s_waitcnt lgkmcnt(4)
	v_mfma_f32_16x16x32_bf16 v[16:19], v[232:235], v[236:239], v[16:19]
	ds_read_b32 v232, v109
	s_waitcnt lgkmcnt(3)
	v_mfma_f32_16x16x32_bf16 v[20:23], v[244:247], v[240:243], v[20:23]
	s_waitcnt lgkmcnt(2)
	v_mfma_f32_16x16x32_bf16 v[16:19], v[244:247], v[248:251], v[16:19]
	s_waitcnt lgkmcnt(0)
	v_sub_f32_e32 v24, v232, v228
	v_min_f32_e32 v24, 0, v24
	v_mul_f32_e32 v24, 0x3fb8aa3b, v24
	v_exp_f32_e32 v24, v24
	s_nop 0
	s_nop 1
	v_mul_f32_e32 v29, v16, v24
	v_sub_f32_e32 v16, v232, v229
	v_min_f32_e32 v16, 0, v16
	v_mul_f32_e32 v16, 0x3fb8aa3b, v16
	v_exp_f32_e32 v16, v16
	v_mul_f32_e32 v20, v20, v24
	v_mov_b32_e32 v24, v21
	v_mov_b32_e32 v25, v22
	v_mul_f32_e32 v30, v17, v16
	v_sub_f32_e32 v17, v232, v230
	v_min_f32_e32 v17, 0, v17
	v_mul_f32_e32 v17, 0x3fb8aa3b, v17
	v_exp_f32_e32 v17, v17
	v_cndmask_b32_e64 v20, 0, v20, s[54:55]
	v_pk_mul_f32 v[24:25], v[24:25], v[16:17]
	v_sub_f32_e32 v16, v232, v231
	v_min_f32_e32 v16, 0, v16
	v_mul_f32_e32 v16, 0x3fb8aa3b, v16
	v_exp_f32_e32 v16, v16
	v_cndmask_b32_e64 v21, 0, v24, s[60:61]
	v_mul_f32_e32 v24, v18, v17
	v_cndmask_b32_e64 v22, 0, v25, s[58:59]
	v_mul_f32_e32 v17, v23, v16
	v_cndmask_b32_e64 v23, 0, v17, s[64:65]
	v_mul_f32_e32 v19, v19, v16
	v_cvt_pk_bf16_f32 v16, v20, v21
	v_cvt_pk_bf16_f32 v17, v22, v23
	ds_write_b128 v144, v[20:23]
	ds_write_b64 v145, v[16:17]
	ds_read_b128 v[236:239], v198
	ds_read_b128 v[240:243], v107 offset:17408
	ds_read_b128 v[244:247], v107 offset:34816
	ds_read_b128 v[248:251], v198 offset:64
	ds_read_b128 v[228:231], v107 offset:17472
	ds_read_b128 v[232:235], v107 offset:34880
	v_cvt_pk_bf16_f32 v16, v29, s0
	v_cvt_pk_bf16_f32 v17, v30, s0
	v_cndmask_b32_e64 v16, v16, 0, s[56:57]
	v_cndmask_b32_e64 v17, 0, v17, s[54:55]
	v_perm_b32 v18, v17, v16, s25
	v_cvt_pk_bf16_f32 v16, v24, s0
	v_cvt_pk_bf16_f32 v17, v19, s0
	v_cndmask_b32_e64 v16, v16, 0, s[62:63]
	v_cndmask_b32_e64 v17, v17, 0, s[66:67]
	v_perm_b32 v19, v17, v16, s25
	v_lshl_add_u64 v[16:17], v[122:123], 0, v[132:133]
	global_store_dwordx2 v[16:17], v[18:19], off
	s_waitcnt lgkmcnt(4)
	v_mfma_f32_16x16x32_bf16 v[22:25], v[236:239], v[240:243], 0
	ds_read_b128 v[240:243], v198 offset:128
	s_waitcnt lgkmcnt(4)
	v_mfma_f32_16x16x32_bf16 v[18:21], v[236:239], v[244:247], 0
	ds_read_b128 v[236:239], v107 offset:17536
	ds_read_b128 v[244:247], v107 offset:34944
	s_waitcnt lgkmcnt(4)
	v_mfma_f32_16x16x32_bf16 v[22:25], v[248:251], v[228:231], v[22:25]
	ds_read_b128 v[228:231], v198 offset:192
	s_waitcnt lgkmcnt(4)
	v_mfma_f32_16x16x32_bf16 v[18:21], v[248:251], v[232:235], v[18:21]
	ds_read_b128 v[248:251], v107 offset:17600
	ds_read_b128 v[232:235], v107 offset:35008
	s_waitcnt lgkmcnt(4)
	v_mfma_f32_16x16x32_bf16 v[22:25], v[240:243], v[236:239], v[22:25]
	ds_read_b128 v[236:239], v146
	s_waitcnt lgkmcnt(4)
	v_mfma_f32_16x16x32_bf16 v[18:21], v[240:243], v[244:247], v[18:21]
	ds_read_b32 v240, v109
	s_waitcnt lgkmcnt(3)
	v_mfma_f32_16x16x32_bf16 v[22:25], v[228:231], v[248:251], v[22:25]
	s_waitcnt lgkmcnt(2)
	v_mfma_f32_16x16x32_bf16 v[18:21], v[228:231], v[232:235], v[18:21]
	s_waitcnt lgkmcnt(0)
	v_sub_f32_e32 v26, v240, v236
	v_min_f32_e32 v26, 0, v26
	v_mul_f32_e32 v26, 0x3fb8aa3b, v26
	v_exp_f32_e32 v26, v26
	s_nop 0
	s_nop 1
	v_mul_f32_e32 v31, v18, v26
	v_sub_f32_e32 v18, v240, v237
	v_min_f32_e32 v18, 0, v18
	v_mul_f32_e32 v18, 0x3fb8aa3b, v18
	v_exp_f32_e32 v18, v18
	v_mul_f32_e32 v22, v22, v26
	v_mov_b32_e32 v26, v23
	v_mov_b32_e32 v27, v24
	v_mul_f32_e32 v122, v19, v18
	v_sub_f32_e32 v19, v240, v238
	v_min_f32_e32 v19, 0, v19
	v_mul_f32_e32 v19, 0x3fb8aa3b, v19
	v_exp_f32_e32 v19, v19
	v_cndmask_b32_e64 v22, 0, v22, s[68:69]
	v_pk_mul_f32 v[26:27], v[26:27], v[18:19]
	v_sub_f32_e32 v18, v240, v239
	v_min_f32_e32 v18, 0, v18
	v_mul_f32_e32 v18, 0x3fb8aa3b, v18
	v_exp_f32_e32 v18, v18
	v_mul_f32_e32 v20, v20, v19
	v_cndmask_b32_e64 v24, 0, v27, s[72:73]
	v_cndmask_b32_e64 v23, 0, v26, s[74:75]
	v_mul_f32_e32 v19, v25, v18
	v_cndmask_b32_e64 v25, 0, v19, s[78:79]
	v_mul_f32_e32 v21, v21, v18
	v_cvt_pk_bf16_f32 v18, v22, v23
	v_cvt_pk_bf16_f32 v19, v24, v25
	ds_write_b128 v144, v[22:25] offset:64
	ds_write_b64 v145, v[18:19] offset:32
	v_cvt_pk_bf16_f32 v18, v31, s0
	v_cvt_pk_bf16_f32 v19, v122, s0
	v_cndmask_b32_e64 v18, v18, 0, s[70:71]
	v_cndmask_b32_e64 v19, 0, v19, s[68:69]
	v_perm_b32 v18, v19, v18, s25
	v_cvt_pk_bf16_f32 v19, v20, s0
	v_cvt_pk_bf16_f32 v20, v21, s0
	v_cndmask_b32_e64 v19, v19, 0, s[76:77]
	v_cndmask_b32_e64 v20, v20, 0, s[80:81]
	v_perm_b32 v19, v20, v19, s25
	global_store_dwordx2 v[16:17], v[18:19], off offset:32
	s_waitcnt lgkmcnt(0)
	s_waitcnt lgkmcnt(0)
	s_barrier
; DI void gdn_prep_item(const P& p, int l, int item, unsigned char* smem) {
;     ...
;     if (tid < 64) {
;         const int I = tid >> 4, cc = tid & 15;
;         float tt[16];
; #pragma unroll
;         for (int r = 0; r < 16; ++r) tt[r] = (r == cc) ? 1.f : 0.f;
; #pragma unroll
;         for (int j = 0; j < 15; ++j) {
;             const float tj = tt[j];
; #pragma unroll
;             for (int r = j + 1; r < 16; ++r) tt[r] -= sL[(16 * I + r) * LS + 16 * I + j] * tj;
;         }
; #pragma unroll
;         for (int r = 0; r < 16; ++r) sTd[(I * 16 + r) * 24 + cc] = f2bf(tt[r]);
;     }
	s_and_saveexec_b64 vcc, s[38:39]
	s_cbranch_execz .LBB0_321
	ds_write_b16 v89, v87
	ds_read_b128 v[228:231], v86 offset:272
	ds_read_b128 v[232:235], v86 offset:544
	ds_read_b128 v[236:239], v86 offset:816
	ds_read_b128 v[240:243], v86 offset:1088
	ds_read_b128 v[244:247], v86 offset:1360
	ds_read_b128 v[248:251], v86 offset:1632
	ds_read_b128 v[202:205], v86 offset:1904
	ds_read_b128 v[206:209], v86 offset:2176
	ds_read_b128 v[210:213], v86 offset:2448
	ds_read_b128 v[122:125], v86 offset:2720
	s_waitcnt lgkmcnt(7)
	v_fma_f32 v16, -v147, v228, v162
	v_fma_f32 v17, -v147, v232, v161
	v_fma_f32 v18, -v147, v236, v160
	v_fma_f32 v17, -v16, v233, v17
	v_fma_f32 v18, -v16, v237, v18
	v_fma_f32 v18, -v17, v238, v18
	ds_read_b128 v[228:231], v86 offset:2992
	ds_read_b128 v[232:235], v86 offset:3264
	ds_read_b128 v[236:239], v86 offset:3536
	s_waitcnt lgkmcnt(8)
	v_fma_f32 v19, -v147, v240, v159
	v_fma_f32 v20, -v147, v244, v158
	v_fma_f32 v19, -v16, v241, v19
	v_fma_f32 v20, -v16, v245, v20
	v_fma_f32 v19, -v17, v242, v19
	v_fma_f32 v20, -v17, v246, v20
	v_fma_f32 v19, -v18, v243, v19
	v_fma_f32 v20, -v18, v247, v20
	ds_read_b128 v[240:243], v86 offset:3808
	ds_read_b128 v[244:247], v86 offset:4080
	s_waitcnt lgkmcnt(8)
	v_fma_f32 v21, -v147, v248, v157
	v_fma_f32 v22, -v147, v202, v156
	v_fma_f32 v21, -v16, v249, v21
	v_fma_f32 v22, -v16, v203, v22
	v_fma_f32 v21, -v17, v250, v21
	v_fma_f32 v22, -v17, v204, v22
	v_fma_f32 v21, -v18, v251, v21
	v_fma_f32 v22, -v18, v205, v22
	ds_read_b128 v[248:251], v86 offset:1376
	ds_read_b128 v[202:205], v86 offset:1648
	s_waitcnt lgkmcnt(8)
	v_fma_f32 v23, -v147, v206, v155
	v_fma_f32 v24, -v147, v210, v154
	v_fma_f32 v23, -v16, v207, v23
	v_fma_f32 v24, -v16, v211, v24
	v_fma_f32 v23, -v17, v208, v23
	v_fma_f32 v24, -v17, v212, v24
	v_fma_f32 v23, -v18, v209, v23
	v_fma_f32 v24, -v18, v213, v24
	ds_read_b128 v[206:209], v86 offset:1920
	ds_read_b128 v[210:213], v86 offset:2192
	s_waitcnt lgkmcnt(8)
	v_fma_f32 v25, -v147, v122, v153
	v_fma_f32 v26, -v147, v228, v152
	v_fma_f32 v25, -v16, v123, v25
	v_fma_f32 v26, -v16, v229, v26
	v_fma_f32 v25, -v17, v124, v25
	v_fma_f32 v26, -v17, v230, v26
	v_fma_f32 v25, -v18, v125, v25
	v_fma_f32 v26, -v18, v231, v26
	ds_read_b128 v[122:125], v86 offset:2464
	ds_read_b128 v[228:231], v86 offset:2736
	s_waitcnt lgkmcnt(8)
	v_fma_f32 v27, -v147, v232, v151
	v_fma_f32 v28, -v147, v236, v150
	v_fma_f32 v27, -v16, v233, v27
	v_fma_f32 v28, -v16, v237, v28
	v_fma_f32 v27, -v17, v234, v27
	v_fma_f32 v28, -v17, v238, v28
	v_fma_f32 v27, -v18, v235, v27
	v_fma_f32 v28, -v18, v239, v28
	ds_read_b128 v[232:235], v86 offset:3008
	ds_read_b128 v[236:239], v86 offset:3280
	s_waitcnt lgkmcnt(8)
	v_fma_f32 v29, -v147, v240, v149
	v_fma_f32 v30, -v147, v244, v148
	v_fma_f32 v29, -v16, v241, v29
	v_fma_f32 v30, -v16, v245, v30
	v_fma_f32 v29, -v17, v242, v29
	v_fma_f32 v30, -v17, v246, v30
	v_fma_f32 v29, -v18, v243, v29
	v_fma_f32 v30, -v18, v247, v30
	ds_read_b128 v[240:243], v86 offset:3552
	ds_read_b128 v[244:247], v86 offset:3824
	s_waitcnt lgkmcnt(7)
	v_fma_f32 v20, -v19, v248, v20
	v_fma_f32 v21, -v19, v202, v21
	v_fma_f32 v22, -v19, v206, v22
	v_fma_f32 v21, -v20, v203, v21
	v_fma_f32 v22, -v20, v207, v22
	v_fma_f32 v22, -v21, v208, v22
	ds_read_b128 v[248:251], v86 offset:4096
	ds_read_b128 v[202:205], v86 offset:2480
	ds_read_b128 v[206:209], v86 offset:2752
	s_waitcnt lgkmcnt(8)
	v_fma_f32 v23, -v19, v210, v23
	v_fma_f32 v24, -v19, v122, v24
	v_fma_f32 v23, -v20, v211, v23
	v_fma_f32 v24, -v20, v123, v24
	v_fma_f32 v23, -v21, v212, v23
	v_fma_f32 v24, -v21, v124, v24
	v_fma_f32 v23, -v22, v213, v23
	v_fma_f32 v24, -v22, v125, v24
	ds_read_b128 v[210:213], v86 offset:3024
	ds_read_b128 v[122:125], v86 offset:3296
	s_waitcnt lgkmcnt(8)
	v_fma_f32 v25, -v19, v228, v25
	v_fma_f32 v26, -v19, v232, v26
	v_fma_f32 v25, -v20, v229, v25
	v_fma_f32 v26, -v20, v233, v26
	v_fma_f32 v25, -v21, v230, v25
	v_fma_f32 v26, -v21, v234, v26
	v_fma_f32 v25, -v22, v231, v25
	v_fma_f32 v26, -v22, v235, v26
	ds_read_b128 v[228:231], v86 offset:3568
	ds_read_b128 v[232:235], v86 offset:3840
	s_waitcnt lgkmcnt(8)
	v_fma_f32 v27, -v19, v236, v27
	v_fma_f32 v28, -v19, v240, v28
	v_fma_f32 v27, -v20, v237, v27
	v_fma_f32 v28, -v20, v241, v28
	v_fma_f32 v27, -v21, v238, v27
	v_fma_f32 v28, -v21, v242, v28
	v_fma_f32 v27, -v22, v239, v27
	v_fma_f32 v28, -v22, v243, v28
	ds_read_b128 v[236:239], v86 offset:4112
	ds_read_b128 v[240:243], v86 offset:3584
	s_waitcnt lgkmcnt(8)
	v_fma_f32 v29, -v19, v244, v29
	v_fma_f32 v30, -v19, v248, v30
	v_fma_f32 v29, -v20, v245, v29
	v_fma_f32 v30, -v20, v249, v30
	v_fma_f32 v29, -v21, v246, v29
	v_fma_f32 v30, -v21, v250, v30
	v_fma_f32 v29, -v22, v247, v29
	v_fma_f32 v30, -v22, v251, v30
	ds_read_b128 v[244:247], v86 offset:3856
	ds_read_b128 v[248:251], v86 offset:4128
	s_waitcnt lgkmcnt(7)
	v_fma_f32 v24, -v23, v202, v24
	v_fma_f32 v25, -v23, v206, v25
	v_fma_f32 v26, -v23, v210, v26
	v_fma_f32 v25, -v24, v207, v25
	v_fma_f32 v26, -v24, v211, v26
	v_fma_f32 v26, -v25, v212, v26
	s_waitcnt lgkmcnt(5)
	v_fma_f32 v27, -v23, v122, v27
	v_fma_f32 v28, -v23, v228, v28
	v_fma_f32 v27, -v24, v123, v27
	v_fma_f32 v28, -v24, v229, v28
	v_fma_f32 v27, -v25, v124, v27
	v_fma_f32 v28, -v25, v230, v28
	v_fma_f32 v27, -v26, v125, v27
	v_fma_f32 v28, -v26, v231, v28
	s_waitcnt lgkmcnt(3)
	v_fma_f32 v29, -v23, v232, v29
	v_fma_f32 v30, -v23, v236, v30
	v_fma_f32 v29, -v24, v233, v29
	v_fma_f32 v30, -v24, v237, v30
	v_fma_f32 v29, -v25, v234, v29
	v_fma_f32 v30, -v25, v238, v30
	v_fma_f32 v29, -v26, v235, v29
	v_fma_f32 v30, -v26, v239, v30
	s_waitcnt lgkmcnt(0)
	v_fma_f32 v28, -v27, v240, v28
	v_fma_f32 v29, -v27, v244, v29
	v_fma_f32 v30, -v27, v248, v30
	v_fma_f32 v29, -v28, v245, v29
	v_fma_f32 v30, -v28, v249, v30
	v_fma_f32 v30, -v29, v250, v30
	v_cvt_pk_bf16_f32 v31, v16, s0
	ds_write_b16 v89, v31 offset:48
	v_cvt_pk_bf16_f32 v31, v17, s0
	ds_write_b16 v89, v31 offset:96
	v_cvt_pk_bf16_f32 v31, v18, s0
	ds_write_b16 v89, v31 offset:144
	v_cvt_pk_bf16_f32 v31, v19, s0
	ds_write_b16 v89, v31 offset:192
	v_cvt_pk_bf16_f32 v31, v20, s0
	ds_write_b16 v89, v31 offset:240
	v_cvt_pk_bf16_f32 v31, v21, s0
	ds_write_b16 v89, v31 offset:288
	v_cvt_pk_bf16_f32 v31, v22, s0
	ds_write_b16 v89, v31 offset:336
	v_cvt_pk_bf16_f32 v31, v23, s0
	ds_write_b16 v89, v31 offset:384
	v_cvt_pk_bf16_f32 v31, v24, s0
	ds_write_b16 v89, v31 offset:432
	v_cvt_pk_bf16_f32 v31, v25, s0
	ds_write_b16 v89, v31 offset:480
	v_cvt_pk_bf16_f32 v31, v26, s0
	ds_write_b16 v89, v31 offset:528
	v_cvt_pk_bf16_f32 v31, v27, s0
	ds_write_b16 v89, v31 offset:576
	v_cvt_pk_bf16_f32 v31, v28, s0
	ds_write_b16 v89, v31 offset:624
	v_cvt_pk_bf16_f32 v31, v29, s0
	ds_write_b16 v89, v31 offset:672
	v_cvt_pk_bf16_f32 v31, v30, s0
	ds_write_b16 v163, v31
	s_branch .LBB0_321
